# conv loop rewrite placed inline; phase-loop back-branch via trampoline
# baseline (speedup 1.0000x reference)
; DI int tid() { int t = __builtin_amdgcn_workitem_id_x(); asm volatile("" : "+v"(t)); return t; }
; DI unsigned pk2(float a, float b) { f32x2 v = {a, b}; return __builtin_bit_cast(unsigned, __builtin_convertvector(v, bf2_t)); }
; DI float bf_lo(unsigned u) { return __uint_as_float(u << 16); }
; DI float bf_hi(unsigned u) { return __uint_as_float(u & 0xffff0000u); }
; DI bf16_t* slotp(const Params& P, int s) { return (bf16_t*)(P.ws + OFF_PROJ + (size_t)s * PROJ_SLOT); }
; DI void conv_pass(const Params& P, int layer) {
;     const bf16_t* cu = slotp(P, SL_CU); bf16_t* bz = slotp(P, SL_BZ);
;     const float* cw = P.conv_w + layer * 3 * 512;
;     for (int idx = blockIdx.x * 512 + tid(); idx < kT * 64; idx += gridDim.x * 512) {
;         const int tok = idx >> 6, c8 = (idx & 63) * 8, pos = tok & (kS - 1);
;         const u32x4 z4 = {0u, 0u, 0u, 0u};
;         const u32x4 c2 = *(const u32x4*)(cu + (size_t)tok * 512 + c8);
;         const u32x4 c1 = pos >= 1 ? *(const u32x4*)(cu + (size_t)(tok - 1) * 512 + c8) : z4;
;         const u32x4 c0 = pos >= 2 ? *(const u32x4*)(cu + (size_t)(tok - 2) * 512 + c8) : z4;
;         const u32x4 bv = *(const u32x4*)(bz + (size_t)tok * 512 + c8);
;         u32x4 o;
; #pragma unroll
;         for (int j = 0; j < 4; ++j) {
;             const int ch = c8 + 2 * j;
;             const float r0 = bf_lo(bv[j]) * (cw[ch] * bf_lo(c0[j]) + cw[512 + ch] * bf_lo(c1[j]) + cw[1024 + ch] * bf_lo(c2[j]));
;             const float r1 = bf_hi(bv[j]) * (cw[ch + 1] * bf_hi(c0[j]) + cw[512 + ch + 1] * bf_hi(c1[j]) + cw[1024 + ch + 1] * bf_hi(c2[j]));
;             o[j] = pk2(r0, r1);
;         }
;         *(u32x4*)(bz + (size_t)tok * 512 + c8) = o;
;     }
; }
.LBB0_68:
	s_and_b64 vcc, exec, s[6:7]
	s_cbranch_vccz .LBB0_77
	v_readlane_b32 s2, v255, 23
	s_cmp_gt_i32 s2, 0
	s_mov_b64 s[6:7], -1
	s_cbranch_scc0 .LBB0_103
	v_mov_b32_e32 v0, v162
	v_readlane_b32 s2, v253, 48
	s_nop 1
	v_add_u32_e32 v24, s2, v0
	s_mov_b32 s2, 0x200000
	v_cmp_gt_i32_e32 vcc, s2, v24
	s_and_saveexec_b64 s[6:7], vcc
	s_mov_b32 s58, s42
	s_cbranch_execz .LBB0_78
	v_readlane_b32 s8, v253, 30
	s_mul_i32 s2, s42, 0x600
	v_readlane_b32 s9, v253, 31
	v_readlane_b32 s36, v254, 62
	s_load_dword s10, s[8:9], 0x0
	v_readlane_b32 s40, v255, 2
	v_readlane_b32 s41, v255, 3
	s_ashr_i32 s3, s2, 31
	v_readlane_b32 s42, v255, 4
	v_readlane_b32 s43, v255, 5
	v_readlane_b32 s44, v255, 6
	v_readlane_b32 s45, v255, 7
	v_readlane_b32 s46, v255, 8
	v_readlane_b32 s47, v255, 9
	v_readlane_b32 s48, v255, 10
	v_readlane_b32 s49, v255, 11
	v_readlane_b32 s50, v255, 12
	v_readlane_b32 s51, v255, 13
	s_mov_b64 s[20:21], s[40:41]
	s_lshl_b64 s[2:3], s[2:3], 2
	s_mov_b64 s[26:27], s[46:47]
	s_add_u32 s8, s26, s2
	s_addc_u32 s9, s27, s3
	v_readlane_b32 s3, v255, 16
	s_mov_b64 s[22:23], s[42:43]
	s_mov_b64 s[24:25], s[44:45]
	s_mov_b64 s[28:29], s[48:49]
	s_mov_b64 s[30:31], s[50:51]
	s_mov_b32 s42, s58
	s_waitcnt lgkmcnt(0)
	s_lshl_b32 s2, s10, 9
	v_lshl_add_u32 v25, v0, 3, s3
	s_lshl_b32 s3, s10, 12
	s_mov_b64 s[10:11], 0
	v_readlane_b32 s37, v254, 63
	v_readlane_b32 s38, v255, 0
	v_readlane_b32 s39, v255, 1
	s_branch .Lconv_fast
.Lconv_fast:
	s_mul_i32 s12, s2, 3
	v_add_u32_e32 v5, s12, v24
	s_mov_b32 s13, 0x200000
	v_cmp_gt_i32_e32 vcc, s13, v5
	s_cbranch_vccz .LBB0_73
	v_readlane_b32 s12, v253, 44
	v_readlane_b32 s13, v253, 45
	v_readlane_b32 s14, v253, 38
	v_readlane_b32 s15, v253, 39
	v_and_b32_e32 v2, 0x1f8, v25
	v_lshlrev_b32_e32 v3, 2, v2
	v_lshlrev_b32_e32 v2, 1, v2
	v_add_u32_e32 v4, 0x1000, v3
	global_load_dwordx4 v[26:29], v3, s[8:9]
	global_load_dwordx4 v[30:33], v3, s[8:9] offset:16
	global_load_dwordx4 v[34:37], v3, s[8:9] offset:2048
	global_load_dwordx4 v[38:41], v3, s[8:9] offset:2064
	global_load_dwordx4 v[42:45], v4, s[8:9]
	global_load_dwordx4 v[46:49], v4, s[8:9] offset:16
.Lconv_loop:
	v_mov_b32_e32 v5, v24
	v_ashrrev_i32_e32 v6, 6, v5
	v_lshl_add_u32 v74, v6, 10, v2
	v_and_b32_e32 v75, 0x1fff, v6
	v_add_u32_e32 v5, s2, v5
	global_load_dwordx4 v[50:53], v74, s[12:13]
	global_load_dwordx4 v[54:57], v74, s[12:13] offset:-1024
	global_load_dwordx4 v[58:61], v74, s[12:13] offset:-2048
	global_load_dwordx4 v[62:65], v74, s[14:15]
	v_ashrrev_i32_e32 v6, 6, v5
	v_lshl_add_u32 v100, v6, 10, v2
	v_and_b32_e32 v101, 0x1fff, v6
	v_add_u32_e32 v5, s2, v5
	global_load_dwordx4 v[76:79], v100, s[12:13]
	global_load_dwordx4 v[80:83], v100, s[12:13] offset:-1024
	global_load_dwordx4 v[84:87], v100, s[12:13] offset:-2048
	global_load_dwordx4 v[88:91], v100, s[14:15]
	v_ashrrev_i32_e32 v6, 6, v5
	v_lshl_add_u32 v126, v6, 10, v2
	v_and_b32_e32 v127, 0x1fff, v6
	v_add_u32_e32 v5, s2, v5
	global_load_dwordx4 v[102:105], v126, s[12:13]
	global_load_dwordx4 v[106:109], v126, s[12:13] offset:-1024
	global_load_dwordx4 v[110:113], v126, s[12:13] offset:-2048
	global_load_dwordx4 v[114:117], v126, s[14:15]
	v_ashrrev_i32_e32 v6, 6, v5
	v_lshl_add_u32 v152, v6, 10, v2
	v_and_b32_e32 v153, 0x1fff, v6
	global_load_dwordx4 v[128:131], v152, s[12:13]
	global_load_dwordx4 v[132:135], v152, s[12:13] offset:-1024
	global_load_dwordx4 v[136:139], v152, s[12:13] offset:-2048
	global_load_dwordx4 v[140:143], v152, s[14:15]
	s_waitcnt vmcnt(12)
	v_cmp_ne_u32_e32 vcc, 0, v75
	v_cmp_lt_u32_e64 s[0:1], 1, v75
	v_lshlrev_b32_e32 v70, 16, v50
	v_and_b32_e32 v71, 0xffff0000, v50
	v_lshlrev_b32_e32 v72, 16, v62
	v_and_b32_e32 v73, 0xffff0000, v62
	v_cndmask_b32_e32 v54, 0, v54, vcc
	v_cndmask_b32_e64 v58, 0, v58, s[0:1]
	v_lshlrev_b32_e32 v68, 16, v54
	v_and_b32_e32 v69, 0xffff0000, v54
	v_lshlrev_b32_e32 v66, 16, v58
	v_and_b32_e32 v67, 0xffff0000, v58
	v_pk_mul_f32 v[68:69], v[34:35], v[68:69]
	s_nop 0
	v_pk_fma_f32 v[68:69], v[26:27], v[66:67], v[68:69]
	s_nop 0
	v_pk_fma_f32 v[68:69], v[42:43], v[70:71], v[68:69]
	s_nop 0
	v_pk_mul_f32 v[68:69], v[68:69], v[72:73]
	s_nop 0
	v_cvt_pk_bf16_f32 v50, v68, v69
	v_lshlrev_b32_e32 v70, 16, v51
	v_and_b32_e32 v71, 0xffff0000, v51
	v_lshlrev_b32_e32 v72, 16, v63
	v_and_b32_e32 v73, 0xffff0000, v63
	v_cndmask_b32_e32 v55, 0, v55, vcc
	v_cndmask_b32_e64 v59, 0, v59, s[0:1]
	v_lshlrev_b32_e32 v68, 16, v55
	v_and_b32_e32 v69, 0xffff0000, v55
	v_lshlrev_b32_e32 v66, 16, v59
	v_and_b32_e32 v67, 0xffff0000, v59
	v_pk_mul_f32 v[68:69], v[36:37], v[68:69]
	s_nop 0
	v_pk_fma_f32 v[68:69], v[28:29], v[66:67], v[68:69]
	s_nop 0
	v_pk_fma_f32 v[68:69], v[44:45], v[70:71], v[68:69]
	s_nop 0
	v_pk_mul_f32 v[68:69], v[68:69], v[72:73]
	s_nop 0
	v_cvt_pk_bf16_f32 v51, v68, v69
	v_lshlrev_b32_e32 v70, 16, v52
	v_and_b32_e32 v71, 0xffff0000, v52
	v_lshlrev_b32_e32 v72, 16, v64
	v_and_b32_e32 v73, 0xffff0000, v64
	v_cndmask_b32_e32 v56, 0, v56, vcc
	v_cndmask_b32_e64 v60, 0, v60, s[0:1]
	v_lshlrev_b32_e32 v68, 16, v56
	v_and_b32_e32 v69, 0xffff0000, v56
	v_lshlrev_b32_e32 v66, 16, v60
	v_and_b32_e32 v67, 0xffff0000, v60
	v_pk_mul_f32 v[68:69], v[38:39], v[68:69]
	s_nop 0
	v_pk_fma_f32 v[68:69], v[30:31], v[66:67], v[68:69]
	s_nop 0
	v_pk_fma_f32 v[68:69], v[46:47], v[70:71], v[68:69]
	s_nop 0
	v_pk_mul_f32 v[68:69], v[68:69], v[72:73]
	s_nop 0
	v_cvt_pk_bf16_f32 v52, v68, v69
	v_lshlrev_b32_e32 v70, 16, v53
	v_and_b32_e32 v71, 0xffff0000, v53
	v_lshlrev_b32_e32 v72, 16, v65
	v_and_b32_e32 v73, 0xffff0000, v65
	v_cndmask_b32_e32 v57, 0, v57, vcc
	v_cndmask_b32_e64 v61, 0, v61, s[0:1]
	v_lshlrev_b32_e32 v68, 16, v57
	v_and_b32_e32 v69, 0xffff0000, v57
	v_lshlrev_b32_e32 v66, 16, v61
	v_and_b32_e32 v67, 0xffff0000, v61
	v_pk_mul_f32 v[68:69], v[40:41], v[68:69]
	s_nop 0
	v_pk_fma_f32 v[68:69], v[32:33], v[66:67], v[68:69]
	s_nop 0
	v_pk_fma_f32 v[68:69], v[48:49], v[70:71], v[68:69]
	s_nop 0
	v_pk_mul_f32 v[68:69], v[68:69], v[72:73]
	s_nop 0
	v_cvt_pk_bf16_f32 v53, v68, v69
	global_store_dwordx4 v74, v[50:53], s[14:15]
	s_waitcnt vmcnt(9)
; DI unsigned pk2(float a, float b) { f32x2 v = {a, b}; return __builtin_bit_cast(unsigned, __builtin_convertvector(v, bf2_t)); }
; DI float bf_lo(unsigned u) { return __uint_as_float(u << 16); }
; DI float bf_hi(unsigned u) { return __uint_as_float(u & 0xffff0000u); }
; DI void conv_pass(const Params& P, int layer) {
;     ...
; #pragma unroll
;         for (int j = 0; j < 4; ++j) {
;             const int ch = c8 + 2 * j;
;             const float r0 = bf_lo(bv[j]) * (cw[ch] * bf_lo(c0[j]) + cw[512 + ch] * bf_lo(c1[j]) + cw[1024 + ch] * bf_lo(c2[j]));
;             const float r1 = bf_hi(bv[j]) * (cw[ch + 1] * bf_hi(c0[j]) + cw[512 + ch + 1] * bf_hi(c1[j]) + cw[1024 + ch + 1] * bf_hi(c2[j]));
;             o[j] = pk2(r0, r1);
;         }
;         *(u32x4*)(bz + (size_t)tok * 512 + c8) = o;
	v_cmp_ne_u32_e32 vcc, 0, v101
	v_cmp_lt_u32_e64 s[0:1], 1, v101
	v_lshlrev_b32_e32 v96, 16, v76
	v_and_b32_e32 v97, 0xffff0000, v76
	v_lshlrev_b32_e32 v98, 16, v88
	v_and_b32_e32 v99, 0xffff0000, v88
	v_cndmask_b32_e32 v80, 0, v80, vcc
	v_cndmask_b32_e64 v84, 0, v84, s[0:1]
	v_lshlrev_b32_e32 v94, 16, v80
	v_and_b32_e32 v95, 0xffff0000, v80
	v_lshlrev_b32_e32 v92, 16, v84
	v_and_b32_e32 v93, 0xffff0000, v84
	v_pk_mul_f32 v[94:95], v[34:35], v[94:95]
	s_nop 0
	v_pk_fma_f32 v[94:95], v[26:27], v[92:93], v[94:95]
	s_nop 0
	v_pk_fma_f32 v[94:95], v[42:43], v[96:97], v[94:95]
	s_nop 0
	v_pk_mul_f32 v[94:95], v[94:95], v[98:99]
	s_nop 0
	v_cvt_pk_bf16_f32 v76, v94, v95
	v_lshlrev_b32_e32 v96, 16, v77
	v_and_b32_e32 v97, 0xffff0000, v77
	v_lshlrev_b32_e32 v98, 16, v89
	v_and_b32_e32 v99, 0xffff0000, v89
	v_cndmask_b32_e32 v81, 0, v81, vcc
	v_cndmask_b32_e64 v85, 0, v85, s[0:1]
	v_lshlrev_b32_e32 v94, 16, v81
	v_and_b32_e32 v95, 0xffff0000, v81
	v_lshlrev_b32_e32 v92, 16, v85
	v_and_b32_e32 v93, 0xffff0000, v85
	v_pk_mul_f32 v[94:95], v[36:37], v[94:95]
	s_nop 0
	v_pk_fma_f32 v[94:95], v[28:29], v[92:93], v[94:95]
	s_nop 0
	v_pk_fma_f32 v[94:95], v[44:45], v[96:97], v[94:95]
	s_nop 0
	v_pk_mul_f32 v[94:95], v[94:95], v[98:99]
	s_nop 0
	v_cvt_pk_bf16_f32 v77, v94, v95
	v_lshlrev_b32_e32 v96, 16, v78
	v_and_b32_e32 v97, 0xffff0000, v78
	v_lshlrev_b32_e32 v98, 16, v90
	v_and_b32_e32 v99, 0xffff0000, v90
	v_cndmask_b32_e32 v82, 0, v82, vcc
	v_cndmask_b32_e64 v86, 0, v86, s[0:1]
	v_lshlrev_b32_e32 v94, 16, v82
	v_and_b32_e32 v95, 0xffff0000, v82
	v_lshlrev_b32_e32 v92, 16, v86
	v_and_b32_e32 v93, 0xffff0000, v86
	v_pk_mul_f32 v[94:95], v[38:39], v[94:95]
	s_nop 0
	v_pk_fma_f32 v[94:95], v[30:31], v[92:93], v[94:95]
	s_nop 0
	v_pk_fma_f32 v[94:95], v[46:47], v[96:97], v[94:95]
	s_nop 0
	v_pk_mul_f32 v[94:95], v[94:95], v[98:99]
	s_nop 0
	v_cvt_pk_bf16_f32 v78, v94, v95
	v_lshlrev_b32_e32 v96, 16, v79
	v_and_b32_e32 v97, 0xffff0000, v79
	v_lshlrev_b32_e32 v98, 16, v91
	v_and_b32_e32 v99, 0xffff0000, v91
	v_cndmask_b32_e32 v83, 0, v83, vcc
	v_cndmask_b32_e64 v87, 0, v87, s[0:1]
	v_lshlrev_b32_e32 v94, 16, v83
	v_and_b32_e32 v95, 0xffff0000, v83
	v_lshlrev_b32_e32 v92, 16, v87
	v_and_b32_e32 v93, 0xffff0000, v87
	v_pk_mul_f32 v[94:95], v[40:41], v[94:95]
	s_nop 0
	v_pk_fma_f32 v[94:95], v[32:33], v[92:93], v[94:95]
	s_nop 0
	v_pk_fma_f32 v[94:95], v[48:49], v[96:97], v[94:95]
	s_nop 0
	v_pk_mul_f32 v[94:95], v[94:95], v[98:99]
	s_nop 0
	v_cvt_pk_bf16_f32 v79, v94, v95
	global_store_dwordx4 v100, v[76:79], s[14:15]
	s_waitcnt vmcnt(6)
	v_cmp_ne_u32_e32 vcc, 0, v127
	v_cmp_lt_u32_e64 s[0:1], 1, v127
	v_lshlrev_b32_e32 v122, 16, v102
	v_and_b32_e32 v123, 0xffff0000, v102
	v_lshlrev_b32_e32 v124, 16, v114
	v_and_b32_e32 v125, 0xffff0000, v114
	v_cndmask_b32_e32 v106, 0, v106, vcc
	v_cndmask_b32_e64 v110, 0, v110, s[0:1]
	v_lshlrev_b32_e32 v120, 16, v106
	v_and_b32_e32 v121, 0xffff0000, v106
	v_lshlrev_b32_e32 v118, 16, v110
	v_and_b32_e32 v119, 0xffff0000, v110
	v_pk_mul_f32 v[120:121], v[34:35], v[120:121]
	s_nop 0
	v_pk_fma_f32 v[120:121], v[26:27], v[118:119], v[120:121]
	s_nop 0
	v_pk_fma_f32 v[120:121], v[42:43], v[122:123], v[120:121]
	s_nop 0
	v_pk_mul_f32 v[120:121], v[120:121], v[124:125]
	s_nop 0
	v_cvt_pk_bf16_f32 v102, v120, v121
	v_lshlrev_b32_e32 v122, 16, v103
	v_and_b32_e32 v123, 0xffff0000, v103
	v_lshlrev_b32_e32 v124, 16, v115
	v_and_b32_e32 v125, 0xffff0000, v115
	v_cndmask_b32_e32 v107, 0, v107, vcc
	v_cndmask_b32_e64 v111, 0, v111, s[0:1]
	v_lshlrev_b32_e32 v120, 16, v107
	v_and_b32_e32 v121, 0xffff0000, v107
	v_lshlrev_b32_e32 v118, 16, v111
	v_and_b32_e32 v119, 0xffff0000, v111
	v_pk_mul_f32 v[120:121], v[36:37], v[120:121]
	s_nop 0
	v_pk_fma_f32 v[120:121], v[28:29], v[118:119], v[120:121]
	s_nop 0
	v_pk_fma_f32 v[120:121], v[44:45], v[122:123], v[120:121]
	s_nop 0
	v_pk_mul_f32 v[120:121], v[120:121], v[124:125]
	s_nop 0
	v_cvt_pk_bf16_f32 v103, v120, v121
	v_lshlrev_b32_e32 v122, 16, v104
	v_and_b32_e32 v123, 0xffff0000, v104
	v_lshlrev_b32_e32 v124, 16, v116
	v_and_b32_e32 v125, 0xffff0000, v116
	v_cndmask_b32_e32 v108, 0, v108, vcc
	v_cndmask_b32_e64 v112, 0, v112, s[0:1]
	v_lshlrev_b32_e32 v120, 16, v108
	v_and_b32_e32 v121, 0xffff0000, v108
	v_lshlrev_b32_e32 v118, 16, v112
	v_and_b32_e32 v119, 0xffff0000, v112
	v_pk_mul_f32 v[120:121], v[38:39], v[120:121]
	s_nop 0
	v_pk_fma_f32 v[120:121], v[30:31], v[118:119], v[120:121]
	s_nop 0
	v_pk_fma_f32 v[120:121], v[46:47], v[122:123], v[120:121]
	s_nop 0
	v_pk_mul_f32 v[120:121], v[120:121], v[124:125]
	s_nop 0
	v_cvt_pk_bf16_f32 v104, v120, v121
	v_lshlrev_b32_e32 v122, 16, v105
	v_and_b32_e32 v123, 0xffff0000, v105
	v_lshlrev_b32_e32 v124, 16, v117
	v_and_b32_e32 v125, 0xffff0000, v117
	v_cndmask_b32_e32 v109, 0, v109, vcc
	v_cndmask_b32_e64 v113, 0, v113, s[0:1]
	v_lshlrev_b32_e32 v120, 16, v109
	v_and_b32_e32 v121, 0xffff0000, v109
	v_lshlrev_b32_e32 v118, 16, v113
	v_and_b32_e32 v119, 0xffff0000, v113
	v_pk_mul_f32 v[120:121], v[40:41], v[120:121]
	s_nop 0
	v_pk_fma_f32 v[120:121], v[32:33], v[118:119], v[120:121]
	s_nop 0
	v_pk_fma_f32 v[120:121], v[48:49], v[122:123], v[120:121]
	s_nop 0
	v_pk_mul_f32 v[120:121], v[120:121], v[124:125]
	s_nop 0
	v_cvt_pk_bf16_f32 v105, v120, v121
	global_store_dwordx4 v126, v[102:105], s[14:15]
	s_waitcnt vmcnt(3)
; DI int tid() { int t = __builtin_amdgcn_workitem_id_x(); asm volatile("" : "+v"(t)); return t; }
; DI unsigned pk2(float a, float b) { f32x2 v = {a, b}; return __builtin_bit_cast(unsigned, __builtin_convertvector(v, bf2_t)); }
; DI float bf_lo(unsigned u) { return __uint_as_float(u << 16); }
; DI float bf_hi(unsigned u) { return __uint_as_float(u & 0xffff0000u); }
; DI void conv_pass(const Params& P, int layer) {
;     ...
;     for (int idx = blockIdx.x * 512 + tid(); idx < kT * 64; idx += gridDim.x * 512) {
;         const int tok = idx >> 6, c8 = (idx & 63) * 8, pos = tok & (kS - 1);
;         const u32x4 z4 = {0u, 0u, 0u, 0u};
;         const u32x4 c2 = *(const u32x4*)(cu + (size_t)tok * 512 + c8);
;         const u32x4 c1 = pos >= 1 ? *(const u32x4*)(cu + (size_t)(tok - 1) * 512 + c8) : z4;
;         const u32x4 c0 = pos >= 2 ? *(const u32x4*)(cu + (size_t)(tok - 2) * 512 + c8) : z4;
;         const u32x4 bv = *(const u32x4*)(bz + (size_t)tok * 512 + c8);
;         u32x4 o;
; #pragma unroll
;         for (int j = 0; j < 4; ++j) {
;             const int ch = c8 + 2 * j;
;             const float r0 = bf_lo(bv[j]) * (cw[ch] * bf_lo(c0[j]) + cw[512 + ch] * bf_lo(c1[j]) + cw[1024 + ch] * bf_lo(c2[j]));
;             const float r1 = bf_hi(bv[j]) * (cw[ch + 1] * bf_hi(c0[j]) + cw[512 + ch + 1] * bf_hi(c1[j]) + cw[1024 + ch + 1] * bf_hi(c2[j]));
;             o[j] = pk2(r0, r1);
;         }
;         *(u32x4*)(bz + (size_t)tok * 512 + c8) = o;
;     }
; }
	v_cmp_ne_u32_e32 vcc, 0, v153
	v_cmp_lt_u32_e64 s[0:1], 1, v153
	v_lshlrev_b32_e32 v148, 16, v128
	v_and_b32_e32 v149, 0xffff0000, v128
	v_lshlrev_b32_e32 v150, 16, v140
	v_and_b32_e32 v151, 0xffff0000, v140
	v_cndmask_b32_e32 v132, 0, v132, vcc
	v_cndmask_b32_e64 v136, 0, v136, s[0:1]
	v_lshlrev_b32_e32 v146, 16, v132
	v_and_b32_e32 v147, 0xffff0000, v132
	v_lshlrev_b32_e32 v144, 16, v136
	v_and_b32_e32 v145, 0xffff0000, v136
	v_pk_mul_f32 v[146:147], v[34:35], v[146:147]
	s_nop 0
	v_pk_fma_f32 v[146:147], v[26:27], v[144:145], v[146:147]
	s_nop 0
	v_pk_fma_f32 v[146:147], v[42:43], v[148:149], v[146:147]
	s_nop 0
	v_pk_mul_f32 v[146:147], v[146:147], v[150:151]
	s_nop 0
	v_cvt_pk_bf16_f32 v128, v146, v147
	v_lshlrev_b32_e32 v148, 16, v129
	v_and_b32_e32 v149, 0xffff0000, v129
	v_lshlrev_b32_e32 v150, 16, v141
	v_and_b32_e32 v151, 0xffff0000, v141
	v_cndmask_b32_e32 v133, 0, v133, vcc
	v_cndmask_b32_e64 v137, 0, v137, s[0:1]
	v_lshlrev_b32_e32 v146, 16, v133
	v_and_b32_e32 v147, 0xffff0000, v133
	v_lshlrev_b32_e32 v144, 16, v137
	v_and_b32_e32 v145, 0xffff0000, v137
	v_pk_mul_f32 v[146:147], v[36:37], v[146:147]
	s_nop 0
	v_pk_fma_f32 v[146:147], v[28:29], v[144:145], v[146:147]
	s_nop 0
	v_pk_fma_f32 v[146:147], v[44:45], v[148:149], v[146:147]
	s_nop 0
	v_pk_mul_f32 v[146:147], v[146:147], v[150:151]
	s_nop 0
	v_cvt_pk_bf16_f32 v129, v146, v147
	v_lshlrev_b32_e32 v148, 16, v130
	v_and_b32_e32 v149, 0xffff0000, v130
	v_lshlrev_b32_e32 v150, 16, v142
	v_and_b32_e32 v151, 0xffff0000, v142
	v_cndmask_b32_e32 v134, 0, v134, vcc
	v_cndmask_b32_e64 v138, 0, v138, s[0:1]
	v_lshlrev_b32_e32 v146, 16, v134
	v_and_b32_e32 v147, 0xffff0000, v134
	v_lshlrev_b32_e32 v144, 16, v138
	v_and_b32_e32 v145, 0xffff0000, v138
	v_pk_mul_f32 v[146:147], v[38:39], v[146:147]
	s_nop 0
	v_pk_fma_f32 v[146:147], v[30:31], v[144:145], v[146:147]
	s_nop 0
	v_pk_fma_f32 v[146:147], v[46:47], v[148:149], v[146:147]
	s_nop 0
	v_pk_mul_f32 v[146:147], v[146:147], v[150:151]
	s_nop 0
	v_cvt_pk_bf16_f32 v130, v146, v147
	v_lshlrev_b32_e32 v148, 16, v131
	v_and_b32_e32 v149, 0xffff0000, v131
	v_lshlrev_b32_e32 v150, 16, v143
	v_and_b32_e32 v151, 0xffff0000, v143
	v_cndmask_b32_e32 v135, 0, v135, vcc
	v_cndmask_b32_e64 v139, 0, v139, s[0:1]
	v_lshlrev_b32_e32 v146, 16, v135
	v_and_b32_e32 v147, 0xffff0000, v135
	v_lshlrev_b32_e32 v144, 16, v139
	v_and_b32_e32 v145, 0xffff0000, v139
	v_pk_mul_f32 v[146:147], v[40:41], v[146:147]
	s_nop 0
	v_pk_fma_f32 v[146:147], v[32:33], v[144:145], v[146:147]
	s_nop 0
	v_pk_fma_f32 v[146:147], v[48:49], v[148:149], v[146:147]
	s_nop 0
	v_pk_mul_f32 v[146:147], v[146:147], v[150:151]
	s_nop 0
	v_cvt_pk_bf16_f32 v131, v146, v147
	global_store_dwordx4 v152, v[128:131], s[14:15]
	s_lshl_b32 s0, s2, 2
	s_lshl_b32 s1, s3, 2
	v_add_u32_e32 v24, s0, v24
	v_add_u32_e32 v25, s1, v25
	s_mul_i32 s0, s2, 3
	s_mov_b32 s1, 0x200000
	v_add_u32_e32 v5, s0, v24
	v_cmp_gt_i32_e32 vcc, s1, v5
	s_cbranch_vccnz .Lconv_loop
	v_cmp_gt_i32_e32 vcc, s1, v24
	s_and_b64 exec, exec, vcc
	s_cbranch_execz .LBB0_78
	s_branch .LBB0_73
.LBB0_72:
	s_or_b64 exec, exec, s[12:13]
	v_readlane_b32 s12, v253, 38
	v_lshlrev_b64 v[14:15], 9, v[14:15]
	v_readlane_b32 s13, v253, 39
	s_waitcnt vmcnt(0)
	v_lshlrev_b32_e32 v44, 16, v6
	v_and_b32_e32 v45, 0xffff0000, v6
	v_lshl_add_u64 v[14:15], v[14:15], 1, s[12:13]
	v_lshl_add_u64 v[22:23], v[14:15], 0, v[0:1]
	v_lshlrev_b32_e32 v0, 2, v16
	global_load_dwordx4 v[26:29], v[22:23], off
	global_load_dwordx4 v[14:17], v0, s[8:9] offset:16
	global_load_dwordx4 v[30:33], v0, s[8:9]
	global_load_dwordx4 v[18:21], v0, s[8:9] offset:2064
	global_load_dwordx4 v[34:37], v0, s[8:9] offset:2048
	v_lshl_add_u64 v[38:39], s[8:9], 0, v[0:1]
	s_mov_b64 s[12:13], 0x1000
	v_lshl_add_u64 v[42:43], v[38:39], 0, s[12:13]
	v_lshlrev_b32_e32 v40, 16, v10
	v_and_b32_e32 v41, 0xffff0000, v10
	s_movk_i32 s12, 0x1000
	v_lshlrev_b32_e32 v6, 16, v7
	v_and_b32_e32 v7, 0xffff0000, v7
	v_lshlrev_b32_e32 v10, 16, v11
	v_and_b32_e32 v11, 0xffff0000, v11
	v_add_u32_e32 v24, s2, v24
	v_add_u32_e32 v25, s3, v25
	s_waitcnt vmcnt(4)
	v_lshlrev_b32_e32 v46, 16, v26
	v_and_b32_e32 v47, 0xffff0000, v26
	s_waitcnt vmcnt(0)
	v_pk_mul_f32 v[34:35], v[34:35], v[44:45]
	v_pk_mul_f32 v[6:7], v[36:37], v[6:7]
	v_pk_fma_f32 v[30:31], v[30:31], v[40:41], v[34:35]
	v_add_co_u32_e32 v34, vcc, s12, v38
	v_pk_fma_f32 v[6:7], v[32:33], v[10:11], v[6:7]
	s_nop 0
	v_addc_co_u32_e32 v35, vcc, 0, v39, vcc
	global_load_dwordx4 v[38:41], v[34:35], off
	s_nop 0
	global_load_dwordx4 v[42:45], v[42:43], off offset:16
	v_lshlrev_b32_e32 v10, 16, v3
	v_and_b32_e32 v11, 0xffff0000, v3
	v_lshlrev_b32_e32 v26, 16, v27
	v_and_b32_e32 v27, 0xffff0000, v27
	v_lshlrev_b32_e32 v34, 16, v2
	v_and_b32_e32 v35, 0xffff0000, v2
	s_mov_b32 s12, 0x1fffff
	v_cmp_lt_i32_e32 vcc, s12, v24
	s_or_b64 s[10:11], vcc, s[10:11]
	s_waitcnt vmcnt(1)
	v_pk_fma_f32 v[6:7], v[40:41], v[10:11], v[6:7]
	s_nop 0
	v_pk_mul_f32 v[6:7], v[6:7], v[26:27]
	v_lshlrev_b32_e32 v26, 16, v8
	v_and_b32_e32 v27, 0xffff0000, v8
	v_lshlrev_b32_e32 v10, 16, v12
	v_and_b32_e32 v11, 0xffff0000, v12
	v_pk_mul_f32 v[18:19], v[18:19], v[26:27]
	v_cvt_pk_bf16_f32 v3, v6, v7
	v_pk_fma_f32 v[10:11], v[14:15], v[10:11], v[18:19]
	v_lshlrev_b32_e32 v14, 16, v4
	v_and_b32_e32 v15, 0xffff0000, v4
	v_lshlrev_b32_e32 v6, 16, v28
	v_and_b32_e32 v7, 0xffff0000, v28
	s_waitcnt vmcnt(0)
	v_pk_fma_f32 v[10:11], v[42:43], v[14:15], v[10:11]
	v_lshlrev_b32_e32 v8, 16, v9
	v_and_b32_e32 v9, 0xffff0000, v9
	v_pk_mul_f32 v[6:7], v[10:11], v[6:7]
	v_lshlrev_b32_e32 v10, 16, v13
	v_and_b32_e32 v11, 0xffff0000, v13
	v_pk_mul_f32 v[8:9], v[20:21], v[8:9]
	v_pk_fma_f32 v[30:31], v[38:39], v[34:35], v[30:31]
	v_pk_fma_f32 v[8:9], v[16:17], v[10:11], v[8:9]
	v_lshlrev_b32_e32 v10, 16, v5
	v_and_b32_e32 v11, 0xffff0000, v5
	v_cvt_pk_bf16_f32 v4, v6, v7
	v_lshlrev_b32_e32 v6, 16, v29
	v_and_b32_e32 v7, 0xffff0000, v29
	v_pk_fma_f32 v[8:9], v[44:45], v[10:11], v[8:9]
	v_pk_mul_f32 v[30:31], v[30:31], v[46:47]
	v_pk_mul_f32 v[6:7], v[8:9], v[6:7]
	v_cvt_pk_bf16_f32 v2, v30, v31
	v_cvt_pk_bf16_f32 v5, v6, v7
	global_store_dwordx4 v[22:23], v[2:5], off
	s_andn2_b64 exec, exec, s[10:11]
	s_cbranch_execz .LBB0_78

; #define LAS __attribute__((address_space(3)))
; DI unsigned xb_xcc_id() { return (unsigned)__builtin_amdgcn_s_getreg((3 << 11) | 20) & 0xFu; }
; __global__ void __launch_bounds__(512) fwd_megakernel(Params P) {
;     ...
;     for (int ph = P.ph_lo; ph < P.ph_hi; ++ph) {
;         run_phase(P, ph, smem);
;         if (ph + 1 < P.ph_hi) {
;             if (ph == P.ph_lo) { cg::this_grid().sync(); (void)xcd_barrier_post((unsigned*)(P.ws + OFF_BAR), (volatile LAS unsigned*)(smem + LDS_XB)); }
;             else { XcdBarrier xb; xb.bar = (unsigned*)(P.ws + OFF_BAR); xb.x = xb_xcc_id(); xb.st = (volatile LAS unsigned*)(smem + LDS_XB); xcd_barrier(xb); }
;         }
;     }
.Lhop15:
	s_branch .LBB0_15
